# prep phase: causal depthwise conv loop rewritten by hand (all four tap rows loaded together, weights and bias hoisted out of the loop); scan1 on 224 CUs beside s5_carry on 32 CUs
# speedup vs baseline: 1.0348x; 1.0198x over previous
; #define LAS __attribute__((address_space(3)))
; __device__ __forceinline__ int opaque_tid() { int t = threadIdx.x; asm volatile("" : "+v"(t)); return t; }
; __device__ __forceinline__ unsigned cvt_pk_bf16(float lo, float hi) { unsigned r; asm volatile("v_cvt_pk_bf16_f32 %0, %1, %2" : "=v"(r) : "v"(lo), "v"(hi)); return r; }
; __device__ __forceinline__ float bf_lo(unsigned w) { return __uint_as_float(w << 16); }
; __device__ __forceinline__ float bf_hi(unsigned w) { return __uint_as_float(w & 0xffff0000u); }
; __device__ __forceinline__ void phase_prep(LAS unsigned char* lds, const bf16_t* p5, bf16_t* xc, bf16_t* vt, const float* cw, const float* cb) {
;     const int tid = opaque_tid(); const int gt = blockIdx.x * 512 + tid, NGT = gridDim.x * 512;
;     for (int it = gt; it < MP * 128; it += NGT) {
;         const int m = it >> 7, c0 = (it & 127) * 8; float o[8];
; #pragma unroll
;         for (int j = 0; j < 8; ++j) o[j] = cb[c0 + j];
; #pragma unroll
;         for (int k = 0; k < 4; ++k) { const int mm = m - 3 + k; if (mm >= 0) {
;                 const u32x4 a = *(const u32x4*)(p5 + (size_t)mm * LDP + C_AX + c0);
;                 const float av[8] = {bf_lo(a.x), bf_hi(a.x), bf_lo(a.y), bf_hi(a.y), bf_lo(a.z), bf_hi(a.z), bf_lo(a.w), bf_hi(a.w)};
; #pragma unroll
;                 for (int j = 0; j < 8; ++j) o[j] += cw[k * 1024 + c0 + j] * av[j]; } }
;         u32x4 w; w.x = cvt_pk_bf16(o[0], o[1]); w.y = cvt_pk_bf16(o[2], o[3]); w.z = cvt_pk_bf16(o[4], o[5]); w.w = cvt_pk_bf16(o[6], o[7]);
;         *(u32x4*)(xc + (size_t)m * 1024 + c0) = w;
;     }
.LBB0_412:
	s_or_b64 exec, exec, s[4:5]
	v_mov_b32_e32 v0, v162
	s_waitcnt lgkmcnt(0)
	v_mov_b32_e32 v2, v163
	s_barrier
	v_mov_b32_e32 v14, v208
	v_readfirstlane_b32 s14, v0
	v_mov_b32_e32 v0, v1
	v_readlane_b32 s16, v252, 4
	v_readfirstlane_b32 s15, v2
	s_add_u32 s4, s14, 0x8900000
	v_readfirstlane_b32 s24, v0
	v_add_u32_e32 v15, s16, v14
	s_mov_b32 s16, 0x208000
	s_addc_u32 s5, s15, 0
	v_cmp_gt_i32_e32 vcc, s16, v15
	s_and_saveexec_b64 s[16:17], vcc
	s_cbranch_execz .LBB0_423
	s_lshl_b64 s[34:35], s[40:41], 14
	s_add_u32 s18, s14, 0x1ef00000
	s_addc_u32 s19, s15, 0
	s_ashr_i32 s25, s24, 31
	s_lshl_b64 s[24:25], s[24:25], 3
	v_readlane_b32 s28, v254, 30
	v_readlane_b32 s29, v254, 31
	s_add_u32 s24, s28, s24
	s_addc_u32 s25, s29, s25
	s_load_dwordx4 s[28:31], s[24:25], 0x28
	v_readlane_b32 s24, v254, 13
	s_nop 1
	v_lshl_add_u32 v16, v14, 3, s24
	s_waitcnt lgkmcnt(0)
	s_add_u32 s24, s28, s34
	s_addc_u32 s25, s29, s35
	s_add_u32 s0, s30, s0
	s_addc_u32 s1, s31, s1
	v_and_b32_e32 v100, 0x7f, v15
	v_lshlrev_b32_e32 v101, 5, v100
	v_lshlrev_b32_e32 v102, 4, v100
	global_load_dwordx4 v[20:23], v101, s[0:1]
	global_load_dwordx4 v[24:27], v101, s[0:1] offset:16
	global_load_dwordx4 v[28:31], v101, s[24:25]
	global_load_dwordx4 v[32:35], v101, s[24:25] offset:16
	v_add_u32_e32 v103, 0x1000, v101
	global_load_dwordx4 v[36:39], v103, s[24:25]
	global_load_dwordx4 v[40:43], v103, s[24:25] offset:16
	v_add_u32_e32 v103, 0x2000, v101
	global_load_dwordx4 v[44:47], v103, s[24:25]
	global_load_dwordx4 v[48:51], v103, s[24:25] offset:16
	v_add_u32_e32 v103, 0x3000, v101
	global_load_dwordx4 v[52:55], v103, s[24:25]
	global_load_dwordx4 v[56:59], v103, s[24:25] offset:16
	v_lshrrev_b32_e32 v105, 7, v15
	s_add_u32 s46, s4, 0x800
	s_addc_u32 s47, s5, 0
	s_movk_i32 s28, 0x2800
	v_mad_u32_u24 v109, v105, s28, v102
	v_add_u32_e32 v108, 0xffffd800, v109
	v_add_u32_e32 v107, 0xffffb000, v109
	v_add_u32_e32 v106, 0xffff8800, v109
	v_lshl_add_u32 v110, v105, 11, v102
.Lcv_loop:
	v_cmp_lt_u32_e64 s[50:51], 2, v105
	v_cmp_lt_u32_e64 s[52:53], 1, v105
	v_cmp_lt_u32_e64 s[54:55], 0, v105
	s_nop 1
	v_cndmask_b32_e64 v103, v102, v106, s[50:51]
	v_cndmask_b32_e64 v104, v102, v107, s[52:53]
	v_cndmask_b32_e64 v111, v102, v108, s[54:55]
	global_load_dwordx4 v[60:63], v103, s[46:47]
	global_load_dwordx4 v[64:67], v104, s[46:47]
	global_load_dwordx4 v[68:71], v111, s[46:47]
	global_load_dwordx4 v[72:75], v109, s[46:47]
	s_waitcnt vmcnt(0)
	v_cndmask_b32_e64 v60, 0, v60, s[50:51]
	v_cndmask_b32_e64 v61, 0, v61, s[50:51]
	v_cndmask_b32_e64 v62, 0, v62, s[50:51]
	v_cndmask_b32_e64 v63, 0, v63, s[50:51]
	v_cndmask_b32_e64 v64, 0, v64, s[52:53]
	v_cndmask_b32_e64 v65, 0, v65, s[52:53]
	v_cndmask_b32_e64 v66, 0, v66, s[52:53]
	v_cndmask_b32_e64 v67, 0, v67, s[52:53]
	v_cndmask_b32_e64 v68, 0, v68, s[54:55]
	v_cndmask_b32_e64 v69, 0, v69, s[54:55]
	v_cndmask_b32_e64 v70, 0, v70, s[54:55]
	v_cndmask_b32_e64 v71, 0, v71, s[54:55]
	v_lshlrev_b32_e32 v112, 16, v60
	v_and_b32_e32 v113, 0xffff0000, v60
	v_lshlrev_b32_e32 v114, 16, v61
	v_and_b32_e32 v115, 0xffff0000, v61
	v_lshlrev_b32_e32 v116, 16, v62
	v_and_b32_e32 v117, 0xffff0000, v62
	v_lshlrev_b32_e32 v118, 16, v63
	v_and_b32_e32 v119, 0xffff0000, v63
	v_fma_f32 v92, v28, v112, v20
	v_fma_f32 v93, v29, v113, v21
	v_fma_f32 v94, v30, v114, v22
	v_fma_f32 v95, v31, v115, v23
	v_fma_f32 v96, v32, v116, v24
	v_fma_f32 v97, v33, v117, v25
	v_fma_f32 v98, v34, v118, v26
	v_fma_f32 v99, v35, v119, v27
	v_lshlrev_b32_e32 v112, 16, v64
	v_and_b32_e32 v113, 0xffff0000, v64
	v_lshlrev_b32_e32 v114, 16, v65
	v_and_b32_e32 v115, 0xffff0000, v65
	v_lshlrev_b32_e32 v116, 16, v66
	v_and_b32_e32 v117, 0xffff0000, v66
	v_lshlrev_b32_e32 v118, 16, v67
	v_and_b32_e32 v119, 0xffff0000, v67
	v_fma_f32 v92, v36, v112, v92
	v_fma_f32 v93, v37, v113, v93
	v_fma_f32 v94, v38, v114, v94
	v_fma_f32 v95, v39, v115, v95
	v_fma_f32 v96, v40, v116, v96
	v_fma_f32 v97, v41, v117, v97
	v_fma_f32 v98, v42, v118, v98
	v_fma_f32 v99, v43, v119, v99
	v_lshlrev_b32_e32 v112, 16, v68
	v_and_b32_e32 v113, 0xffff0000, v68
	v_lshlrev_b32_e32 v114, 16, v69
	v_and_b32_e32 v115, 0xffff0000, v69
	v_lshlrev_b32_e32 v116, 16, v70
	v_and_b32_e32 v117, 0xffff0000, v70
	v_lshlrev_b32_e32 v118, 16, v71
	v_and_b32_e32 v119, 0xffff0000, v71
	v_fma_f32 v92, v44, v112, v92
	v_fma_f32 v93, v45, v113, v93
	v_fma_f32 v94, v46, v114, v94
	v_fma_f32 v95, v47, v115, v95
	v_fma_f32 v96, v48, v116, v96
	v_fma_f32 v97, v49, v117, v97
	v_fma_f32 v98, v50, v118, v98
	v_fma_f32 v99, v51, v119, v99
	v_lshlrev_b32_e32 v112, 16, v72
	v_and_b32_e32 v113, 0xffff0000, v72
	v_lshlrev_b32_e32 v114, 16, v73
	v_and_b32_e32 v115, 0xffff0000, v73
	v_lshlrev_b32_e32 v116, 16, v74
	v_and_b32_e32 v117, 0xffff0000, v74
	v_lshlrev_b32_e32 v118, 16, v75
	v_and_b32_e32 v119, 0xffff0000, v75
	v_fma_f32 v92, v52, v112, v92
	v_fma_f32 v93, v53, v113, v93
	v_fma_f32 v94, v54, v114, v94
	v_fma_f32 v95, v55, v115, v95
	v_fma_f32 v96, v56, v116, v96
	v_fma_f32 v97, v57, v117, v97
	v_fma_f32 v98, v58, v118, v98
	v_fma_f32 v99, v59, v119, v99
	v_cvt_pk_bf16_f32 v92, v92, v93
	v_cvt_pk_bf16_f32 v93, v94, v95
	v_cvt_pk_bf16_f32 v94, v96, v97
	v_cvt_pk_bf16_f32 v95, v98, v99
	s_nop 0
	global_store_dwordx4 v110, v[92:95], s[18:19]
	v_add_u32_e32 v106, 0xa00000, v106
	v_add_u32_e32 v107, 0xa00000, v107
	v_add_u32_e32 v108, 0xa00000, v108
	v_add_u32_e32 v109, 0xa00000, v109
	v_add_u32_e32 v110, 0x200000, v110
	v_add_u32_e32 v105, 0x400, v105
	v_add_u32_e32 v15, 0x20000, v15
	v_cmp_gt_i32_e32 vcc, 0x208000, v15
	s_nop 1
	s_and_b64 exec, exec, vcc
	s_cbranch_execnz .Lcv_loop

; __device__ __forceinline__ int opaque_tid() { int t = threadIdx.x; asm volatile("" : "+v"(t)); return t; }
; __device__ __forceinline__ void lru_scan1(const bf16_t* p5, const bf16_t* bbuf, float* agg) {
;     const int gt = blockIdx.x * 512 + opaque_tid(), NGT = gridDim.x * 512;
;     for (int it = gt; it < NB * NCH64 * 512; it += NGT) {
;         const int cp = it & 511, bc = it >> 9; const int b = bc / NCH64, c = bc - b * NCH64; const size_t m0 = (size_t)b * TP + c * 64;
.LBB0_846:
	s_or_b64 exec, exec, s[0:1]
	v_mov_b32_e32 v0, v163
	s_waitcnt lgkmcnt(0)
	v_mov_b32_e32 v2, v162
	s_barrier
	v_readlane_b32 s4, v252, 4
	s_nop 3
	s_cmpk_lt_u32 s2, 0xe0
	s_cselect_b32 s4, s4, 0x20800
	v_readfirstlane_b32 s1, v0
	v_mov_b32_e32 v0, v1
	v_readfirstlane_b32 s0, v2
	v_readfirstlane_b32 s14, v0
	v_mov_b32_e32 v0, v208
	s_nop 0
	v_add_u32_e32 v18, s4, v0
	s_mov_b32 s4, 0x20800
	v_cmp_gt_i32_e32 vcc, s4, v18
	s_and_saveexec_b64 s[4:5], vcc
	s_cbranch_execz .LBB0_851
	v_and_b32_e32 v2, 0x1ff, v0
	v_lshlrev_b32_e32 v0, 2, v2
	v_lshlrev_b32_e32 v2, 4, v2
	v_mov_b32_e32 v3, v1
	v_lshl_add_u64 v[2:3], s[0:1], 0, v[2:3]
	s_mov_b64 s[16:17], 0x2b600000
	v_lshl_add_u64 v[6:7], v[2:3], 0, s[16:17]
	s_mov_b64 s[16:17], 0

; __device__ __forceinline__ float bf_lo(unsigned w) { return __uint_as_float(w << 16); }
; __device__ __forceinline__ float bf_hi(unsigned w) { return __uint_as_float(w & 0xffff0000u); }
; __device__ __forceinline__ void lru_scan1(const bf16_t* p5, const bf16_t* bbuf, float* agg) {
;     ...
;         for (int t0 = 0; t0 < 64; t0 += 16) {
;             unsigned lw[16], bw[16];
; #pragma unroll
;             for (int k = 0; k < 16; ++k) { lw[k] = *(const unsigned*)(p5 + (m0 + t0 + k) * LDP + C_AX + 2 * cp); bw[k] = *(const unsigned*)(bbuf + (m0 + t0 + k) * 1024 + 2 * cp); }
; #pragma unroll
;             for (int k = 0; k < 16; ++k) { const float l0 = bf_lo(lw[k]), l1 = bf_hi(lw[k]); s0 += l0; s1 += l1; h0 = __expf(l0) * h0 + bf_lo(bw[k]); h1 = __expf(l1) * h1 + bf_hi(bw[k]); }
;         }
.LBB0_849:
	v_lshl_add_u64 v[14:15], v[12:13], 0, v[0:1]
	v_add_co_u32_e32 v20, vcc, 0x8900000, v14
	v_lshl_add_u64 v[16:17], v[10:11], 0, v[0:1]
	s_nop 0
	v_addc_co_u32_e32 v21, vcc, 0, v15, vcc
	v_add_co_u32_e32 v22, vcc, 0x1ef00000, v16
	global_load_dword v9, v[20:21], off offset:2048
	s_nop 0
	v_addc_co_u32_e32 v23, vcc, 0, v17, vcc
	v_add_co_u32_e32 v20, vcc, 0x8903000, v14
	global_load_dword v19, v[22:23], off
	global_load_dword v26, v[22:23], off offset:2048
	v_addc_co_u32_e32 v21, vcc, 0, v15, vcc
	v_add_co_u32_e32 v22, vcc, 0x8905000, v14
	s_add_i32 s15, s15, 16
	s_nop 0
	v_addc_co_u32_e32 v23, vcc, 0, v15, vcc
	v_add_co_u32_e32 v24, vcc, 0x1ef01000, v16
	global_load_dword v27, v[20:21], off
	global_load_dword v28, v[22:23], off offset:2048
	v_addc_co_u32_e32 v25, vcc, 0, v17, vcc
	v_add_co_u32_e32 v20, vcc, 0x8908000, v14
	global_load_dword v29, v[24:25], off
	global_load_dword v30, v[24:25], off offset:2048
	v_addc_co_u32_e32 v21, vcc, 0, v15, vcc
	v_add_co_u32_e32 v22, vcc, 0x890a000, v14
	s_mov_b64 s[18:19], 0x8000
	s_nop 0
	v_addc_co_u32_e32 v23, vcc, 0, v15, vcc
	v_add_co_u32_e32 v24, vcc, 0x1ef02000, v16
	global_load_dword v31, v[20:21], off
	global_load_dword v32, v[22:23], off offset:2048
	v_addc_co_u32_e32 v25, vcc, 0, v17, vcc
	v_add_co_u32_e32 v20, vcc, 0x890d000, v14
	global_load_dword v33, v[24:25], off
	global_load_dword v34, v[24:25], off offset:2048
	v_addc_co_u32_e32 v21, vcc, 0, v15, vcc
	v_add_co_u32_e32 v22, vcc, 0x890f000, v14
	v_lshl_add_u64 v[10:11], v[10:11], 0, s[18:19]
	s_nop 0
	v_addc_co_u32_e32 v23, vcc, 0, v15, vcc
	v_add_co_u32_e32 v24, vcc, 0x1ef03000, v16
	global_load_dword v35, v[20:21], off
	global_load_dword v37, v[22:23], off offset:2048
	v_addc_co_u32_e32 v25, vcc, 0, v17, vcc
	v_add_co_u32_e32 v20, vcc, 0x8912000, v14
	global_load_dword v39, v[24:25], off
	global_load_dword v40, v[24:25], off offset:2048
	v_addc_co_u32_e32 v21, vcc, 0, v15, vcc
	v_add_co_u32_e32 v22, vcc, 0x8914000, v14
	v_lshl_add_u64 v[12:13], v[12:13], 0, s[38:39]
	s_nop 0
	v_addc_co_u32_e32 v23, vcc, 0, v15, vcc
	v_add_co_u32_e32 v24, vcc, 0x1ef04000, v16
	global_load_dword v41, v[20:21], off
	global_load_dword v43, v[22:23], off offset:2048
	v_addc_co_u32_e32 v25, vcc, 0, v17, vcc
	v_add_co_u32_e32 v20, vcc, 0x8917000, v14
	global_load_dword v45, v[24:25], off
	global_load_dword v47, v[24:25], off offset:2048
	v_addc_co_u32_e32 v21, vcc, 0, v15, vcc
	v_add_co_u32_e32 v22, vcc, 0x8919000, v14
	s_cmp_lt_u32 s15, 48
	s_nop 0
	v_addc_co_u32_e32 v23, vcc, 0, v15, vcc
	v_add_co_u32_e32 v24, vcc, 0x1ef05000, v16
	global_load_dword v49, v[20:21], off
	global_load_dword v51, v[22:23], off offset:2048
	v_addc_co_u32_e32 v25, vcc, 0, v17, vcc
	v_add_co_u32_e32 v20, vcc, 0x891c000, v14
	global_load_dword v53, v[24:25], off
	global_load_dword v55, v[24:25], off offset:2048
	v_addc_co_u32_e32 v21, vcc, 0, v15, vcc
	v_add_co_u32_e32 v22, vcc, 0x891e000, v14
	s_waitcnt vmcnt(16)
	v_lshlrev_b32_e32 v48, 16, v30
	v_addc_co_u32_e32 v23, vcc, 0, v15, vcc
	v_add_co_u32_e32 v24, vcc, 0x1ef06000, v16
	global_load_dword v57, v[20:21], off
	global_load_dword v59, v[22:23], off offset:2048
	v_addc_co_u32_e32 v25, vcc, 0, v17, vcc
	v_add_co_u32_e32 v20, vcc, 0x8921000, v14
	global_load_dword v61, v[24:25], off
	global_load_dword v63, v[24:25], off offset:2048
	v_addc_co_u32_e32 v21, vcc, 0, v15, vcc
	v_add_co_u32_e32 v22, vcc, 0x8923000, v14
	v_and_b32_e32 v50, 0xffff0000, v30
	s_nop 0
	v_addc_co_u32_e32 v23, vcc, 0, v15, vcc
	global_load_dword v64, v[20:21], off
	global_load_dword v65, v[22:23], off offset:2048
	v_add_co_u32_e32 v16, vcc, 0x1ef07000, v16
	v_lshlrev_b32_e32 v20, 16, v28
	s_nop 0
	v_addc_co_u32_e32 v17, vcc, 0, v17, vcc
	v_add_co_u32_e32 v14, vcc, 0x8926000, v14
	v_and_b32_e32 v21, 0xffff0000, v26
	s_nop 0
	v_addc_co_u32_e32 v15, vcc, 0, v15, vcc
	global_load_dword v66, v[16:17], off
	global_load_dword v67, v[16:17], off offset:2048
	global_load_dword v68, v[14:15], off
	v_lshlrev_b32_e32 v14, 16, v9
	v_and_b32_e32 v9, 0xffff0000, v9
	v_add_f32_e32 v2, v2, v14
	v_add_f32_e32 v4, v4, v9
	v_mul_f32_e32 v14, 0x3fb8aa3b, v14
	v_mul_f32_e32 v9, 0x3fb8aa3b, v9
	v_exp_f32_e32 v23, v14
	v_exp_f32_e32 v9, v9
	v_lshlrev_b32_e32 v14, 16, v27
	v_and_b32_e32 v16, 0xffff0000, v27
	v_mul_f32_e32 v24, 0x3fb8aa3b, v14
	v_lshlrev_b32_e32 v15, 16, v19
	v_and_b32_e32 v17, 0xffff0000, v19
	v_lshlrev_b32_e32 v19, 16, v26
	v_and_b32_e32 v22, 0xffff0000, v28
	v_mul_f32_e32 v25, 0x3fb8aa3b, v16
	v_mul_f32_e32 v26, 0x3fb8aa3b, v20
	v_exp_f32_e32 v36, v24
	v_mul_f32_e32 v28, 0x3fb8aa3b, v22
	v_exp_f32_e32 v25, v25
	v_exp_f32_e32 v42, v26
	s_waitcnt vmcnt(24)
	v_lshlrev_b32_e32 v24, 16, v31
	v_and_b32_e32 v26, 0xffff0000, v31
	v_exp_f32_e32 v44, v28
	v_fmac_f32_e32 v15, v3, v23
	v_fmac_f32_e32 v17, v5, v9
	s_waitcnt vmcnt(23)
	v_lshlrev_b32_e32 v28, 16, v32
	v_mul_f32_e32 v3, 0x3fb8aa3b, v24
	v_mul_f32_e32 v5, 0x3fb8aa3b, v26
	v_and_b32_e32 v30, 0xffff0000, v32
	v_mul_f32_e32 v9, 0x3fb8aa3b, v28
	v_exp_f32_e32 v3, v3
	v_exp_f32_e32 v5, v5
	s_waitcnt vmcnt(20)
	v_lshlrev_b32_e32 v32, 16, v35
	v_lshlrev_b32_e32 v27, 16, v29
	v_mul_f32_e32 v31, 0x3fb8aa3b, v30
	v_lshlrev_b32_e32 v56, 16, v34
	v_and_b32_e32 v58, 0xffff0000, v34
	v_exp_f32_e32 v9, v9
	v_and_b32_e32 v34, 0xffff0000, v35
	v_fmac_f32_e32 v19, v15, v36
	s_waitcnt vmcnt(19)
	v_lshlrev_b32_e32 v36, 16, v37
	v_mul_f32_e32 v15, 0x3fb8aa3b, v32
	v_and_b32_e32 v29, 0xffff0000, v29
	v_exp_f32_e32 v31, v31
	v_fmac_f32_e32 v21, v17, v25
	v_and_b32_e32 v38, 0xffff0000, v37
	v_mul_f32_e32 v17, 0x3fb8aa3b, v34
	v_fmac_f32_e32 v27, v19, v42
	v_mul_f32_e32 v19, 0x3fb8aa3b, v36
	v_exp_f32_e32 v35, v15
	v_fmac_f32_e32 v29, v21, v44
	v_mul_f32_e32 v21, 0x3fb8aa3b, v38
	s_waitcnt vmcnt(17)
; __device__ __forceinline__ int opaque_tid() { int t = threadIdx.x; asm volatile("" : "+v"(t)); return t; }
; __device__ __forceinline__ float bf_lo(unsigned w) { return __uint_as_float(w << 16); }
; __device__ __forceinline__ float bf_hi(unsigned w) { return __uint_as_float(w & 0xffff0000u); }
; __device__ __forceinline__ void lru_scan1(const bf16_t* p5, const bf16_t* bbuf, float* agg) {
;     ...
;             for (int k = 0; k < 16; ++k) { const float l0 = bf_lo(lw[k]), l1 = bf_hi(lw[k]); s0 += l0; s1 += l1; h0 = __expf(l0) * h0 + bf_lo(bw[k]); h1 = __expf(l1) * h1 + bf_hi(bw[k]); }
;         }
;         *(f32x4*)(agg + ((size_t)bc * 512 + cp) * 4) = (f32x4){s0, h0, s1, h1};
;     }
; __device__ __forceinline__ void s5_carry(bf16_t* xh, const float* sb, const float* lam_re, const float* lam_im, const float* log_step) {
;     const int gt = blockIdx.x * 512 + opaque_tid(), NGT = gridDim.x * 512;
;     for (int it = gt; it < NB * 64 * 64; it += NGT) {
;         const int p = it & 63, g = (it >> 6) & 63, b = it >> 12;
;         const float lr = lam_re[g * 64 + p], li = lam_im[g * 64 + p], step = expf(log_step[g]);
	v_lshlrev_b32_e32 v69, 16, v40
	v_and_b32_e32 v70, 0xffff0000, v40
	v_exp_f32_e32 v52, v17
	v_exp_f32_e32 v19, v19
	s_waitcnt vmcnt(16)
	v_lshlrev_b32_e32 v40, 16, v41
	v_and_b32_e32 v42, 0xffff0000, v41
	v_lshlrev_b32_e32 v23, 16, v33
	v_exp_f32_e32 v21, v21
	v_fmac_f32_e32 v48, v27, v3
	v_fmac_f32_e32 v50, v29, v5
	s_waitcnt vmcnt(15)
	v_lshlrev_b32_e32 v44, 16, v43
	v_and_b32_e32 v46, 0xffff0000, v43
	v_mul_f32_e32 v3, 0x3fb8aa3b, v40
	v_mul_f32_e32 v5, 0x3fb8aa3b, v42
	v_and_b32_e32 v33, 0xffff0000, v33
	v_fmac_f32_e32 v23, v48, v9
	v_mul_f32_e32 v9, 0x3fb8aa3b, v44
	v_mul_f32_e32 v29, 0x3fb8aa3b, v46
	v_exp_f32_e32 v3, v3
	v_exp_f32_e32 v5, v5
	v_lshlrev_b32_e32 v37, 16, v39
	v_fmac_f32_e32 v33, v50, v31
	s_waitcnt vmcnt(14)
	v_lshlrev_b32_e32 v15, 16, v45
	v_and_b32_e32 v17, 0xffff0000, v45
	v_exp_f32_e32 v9, v9
	v_exp_f32_e32 v45, v29
	s_waitcnt vmcnt(12)
	v_lshlrev_b32_e32 v48, 16, v49
	v_fmac_f32_e32 v56, v23, v35
	v_and_b32_e32 v50, 0xffff0000, v49
	v_and_b32_e32 v39, 0xffff0000, v39
	v_fmac_f32_e32 v58, v33, v52
	v_mul_f32_e32 v23, 0x3fb8aa3b, v48
	v_fmac_f32_e32 v37, v56, v19
	v_mul_f32_e32 v19, 0x3fb8aa3b, v50
	v_fmac_f32_e32 v39, v58, v21
	v_exp_f32_e32 v21, v23
	v_exp_f32_e32 v23, v19
	s_waitcnt vmcnt(11)
	v_lshlrev_b32_e32 v52, 16, v51
	v_and_b32_e32 v54, 0xffff0000, v51
	v_fmac_f32_e32 v69, v37, v3
	v_fmac_f32_e32 v70, v39, v5
	v_mul_f32_e32 v29, 0x3fb8aa3b, v52
	v_mul_f32_e32 v31, 0x3fb8aa3b, v54
	v_mul_f32_e32 v3, v69, v9
	v_mul_f32_e32 v5, v70, v45
	v_exp_f32_e32 v29, v29
	v_exp_f32_e32 v31, v31
	v_pk_add_f32 v[2:3], v[2:3], v[14:15]
	v_pk_add_f32 v[4:5], v[4:5], v[16:17]
	s_waitcnt vmcnt(8)
	v_lshlrev_b32_e32 v56, 16, v57
	v_and_b32_e32 v58, 0xffff0000, v57
	v_pk_add_f32 v[14:15], v[2:3], v[20:21]
	v_pk_mul_f32 v[2:3], v[2:3], v[20:21]
	v_pk_add_f32 v[16:17], v[4:5], v[22:23]
	v_pk_mul_f32 v[4:5], v[4:5], v[22:23]
	v_lshlrev_b32_e32 v25, 16, v47
	v_and_b32_e32 v27, 0xffff0000, v47
	v_mul_f32_e32 v9, 0x3fb8aa3b, v56
	v_mul_f32_e32 v19, 0x3fb8aa3b, v58
	v_mov_b32_e32 v15, v3
	v_mov_b32_e32 v17, v5
	v_exp_f32_e32 v37, v9
	v_exp_f32_e32 v39, v19
	v_pk_add_f32 v[14:15], v[14:15], v[24:25]
	v_pk_add_f32 v[16:17], v[16:17], v[26:27]
	s_waitcnt vmcnt(7)
	v_lshlrev_b32_e32 v60, 16, v59
	v_and_b32_e32 v62, 0xffff0000, v59
	s_waitcnt vmcnt(4)
	v_lshlrev_b32_e32 v2, 16, v64
	v_and_b32_e32 v4, 0xffff0000, v64
	s_waitcnt vmcnt(3)
	v_lshlrev_b32_e32 v20, 16, v65
	v_and_b32_e32 v22, 0xffff0000, v65
	v_pk_add_f32 v[64:65], v[14:15], v[28:29]
	v_pk_mul_f32 v[14:15], v[14:15], v[28:29]
	v_pk_add_f32 v[28:29], v[16:17], v[30:31]
	v_pk_mul_f32 v[16:17], v[16:17], v[30:31]
	v_lshlrev_b32_e32 v33, 16, v53
	v_and_b32_e32 v35, 0xffff0000, v53
	v_mul_f32_e32 v45, 0x3fb8aa3b, v60
	v_mul_f32_e32 v47, 0x3fb8aa3b, v62
	v_mov_b32_e32 v65, v15
	v_mov_b32_e32 v29, v17
	v_exp_f32_e32 v45, v45
	v_exp_f32_e32 v47, v47
	v_pk_add_f32 v[14:15], v[64:65], v[32:33]
	v_pk_add_f32 v[16:17], v[28:29], v[34:35]
	v_pk_add_f32 v[28:29], v[14:15], v[36:37]
	v_pk_mul_f32 v[14:15], v[14:15], v[36:37]
	v_pk_add_f32 v[30:31], v[16:17], v[38:39]
	v_pk_mul_f32 v[16:17], v[16:17], v[38:39]
	v_lshlrev_b32_e32 v41, 16, v55
	v_and_b32_e32 v43, 0xffff0000, v55
	v_mul_f32_e32 v9, 0x3fb8aa3b, v2
	v_mul_f32_e32 v19, 0x3fb8aa3b, v4
	v_mov_b32_e32 v29, v15
	v_mov_b32_e32 v31, v17
	v_exp_f32_e32 v53, v9
	v_exp_f32_e32 v55, v19
	v_pk_add_f32 v[14:15], v[28:29], v[40:41]
	v_pk_add_f32 v[16:17], v[30:31], v[42:43]
	v_pk_add_f32 v[28:29], v[14:15], v[44:45]
	v_pk_mul_f32 v[14:15], v[14:15], v[44:45]
	v_pk_add_f32 v[30:31], v[16:17], v[46:47]
	v_pk_mul_f32 v[16:17], v[16:17], v[46:47]
	v_lshlrev_b32_e32 v49, 16, v61
	v_and_b32_e32 v51, 0xffff0000, v61
	v_mul_f32_e32 v21, 0x3fb8aa3b, v20
	v_mul_f32_e32 v23, 0x3fb8aa3b, v22
	v_mov_b32_e32 v29, v15
	v_mov_b32_e32 v31, v17
	v_lshlrev_b32_e32 v57, 16, v63
	v_and_b32_e32 v59, 0xffff0000, v63
	v_exp_f32_e32 v61, v21
	v_exp_f32_e32 v63, v23
	v_pk_add_f32 v[14:15], v[28:29], v[48:49]
	v_pk_add_f32 v[16:17], v[30:31], v[50:51]
	s_waitcnt vmcnt(0)
	v_lshlrev_b32_e32 v24, 16, v68
	v_and_b32_e32 v26, 0xffff0000, v68
	v_pk_add_f32 v[28:29], v[14:15], v[52:53]
	v_pk_mul_f32 v[14:15], v[14:15], v[52:53]
	v_pk_add_f32 v[30:31], v[16:17], v[54:55]
	v_pk_mul_f32 v[16:17], v[16:17], v[54:55]
	v_mul_f32_e32 v9, 0x3fb8aa3b, v24
	v_mul_f32_e32 v19, 0x3fb8aa3b, v26
	v_mov_b32_e32 v29, v15
	v_mov_b32_e32 v31, v17
	v_exp_f32_e32 v21, v9
	v_exp_f32_e32 v23, v19
	v_pk_add_f32 v[14:15], v[28:29], v[56:57]
	v_pk_add_f32 v[16:17], v[30:31], v[58:59]
	v_pk_add_f32 v[28:29], v[14:15], v[60:61]
	v_pk_mul_f32 v[14:15], v[14:15], v[60:61]
	v_pk_add_f32 v[30:31], v[16:17], v[62:63]
	v_pk_mul_f32 v[16:17], v[16:17], v[62:63]
	v_lshlrev_b32_e32 v3, 16, v66
	v_and_b32_e32 v5, 0xffff0000, v66
	v_mov_b32_e32 v29, v15
	v_mov_b32_e32 v31, v17
	v_pk_add_f32 v[2:3], v[28:29], v[2:3]
	v_pk_add_f32 v[4:5], v[30:31], v[4:5]
	v_pk_add_f32 v[14:15], v[2:3], v[20:21]
	v_pk_mul_f32 v[2:3], v[2:3], v[20:21]
	v_pk_add_f32 v[16:17], v[4:5], v[22:23]
	v_pk_mul_f32 v[4:5], v[4:5], v[22:23]
	v_lshlrev_b32_e32 v25, 16, v67
	v_and_b32_e32 v27, 0xffff0000, v67
	v_mov_b32_e32 v15, v3
	v_mov_b32_e32 v17, v5
	v_pk_add_f32 v[2:3], v[14:15], v[24:25]
	v_pk_add_f32 v[4:5], v[16:17], v[26:27]
	s_cbranch_scc1 .LBB0_849
	v_ashrrev_i32_e32 v9, 31, v8
	v_add_u32_e32 v18, 0x1c000, v18
	s_mov_b32 s15, 0x207ff
	v_lshlrev_b64 v[8:9], 13, v[8:9]
	v_cmp_lt_i32_e32 vcc, s15, v18
	v_lshl_add_u64 v[8:9], v[6:7], 0, v[8:9]
	s_or_b64 s[16:17], vcc, s[16:17]
	global_store_dwordx4 v[8:9], v[2:5], off
	s_andn2_b64 exec, exec, s[16:17]
	s_cbranch_execnz .LBB0_848
.LBB0_851:
	s_or_b64 exec, exec, s[4:5]
	v_mov_b32_e32 v0, v208
	s_sub_u32 s4, s2, 0xe0
	s_lshl_b32 s4, s4, 9
	s_cmpk_ge_u32 s2, 0xe0
	s_cselect_b32 s4, s4, 0x4000
	s_nop 1
	v_add_u32_e32 v3, s4, v0
	s_movk_i32 s4, 0x4000
	v_cmp_gt_i32_e32 vcc, s4, v3
	s_and_saveexec_b64 s[4:5], vcc
	s_cbranch_execz .LBB0_860
	s_ashr_i32 s15, s14, 31
	s_lshl_b64 s[14:15], s[14:15], 3
	v_readlane_b32 s16, v254, 30
	v_readlane_b32 s17, v254, 31
	s_add_u32 s14, s16, s14
	s_addc_u32 s15, s17, s15
	s_load_dwordx4 s[16:19], s[14:15], 0x70
	s_load_dwordx2 s[28:29], s[14:15], 0xa8
	v_readlane_b32 s24, v254, 59
	v_readlane_b32 s25, v254, 60
	s_lshl_b64 s[24:25], s[24:25], 2
	s_waitcnt lgkmcnt(0)
	s_add_u32 s14, s16, s24
	s_addc_u32 s15, s17, s25
	s_add_u32 s16, s18, s24
	s_addc_u32 s17, s19, s25
	v_readlane_b32 s18, v254, 61
	v_readlane_b32 s19, v254, 62
	s_lshl_b64 s[18:19], s[18:19], 2
	v_and_b32_e32 v0, 63, v0
	s_add_u32 s18, s28, s18
	s_addc_u32 s19, s29, s19
	v_lshlrev_b32_e32 v2, 2, v0
	v_lshlrev_b32_e32 v4, 3, v0
	s_mov_b64 s[24:25], 0
